# GEMM main loops: the vmcnt and lgkmcnt waits in front of each segment barrier merged into one s_waitcnt (one issue slot less per segment)
# baseline (speedup 1.0000x reference)
.LBB0_211:
	s_add_i32 s38, s8, 2
	s_add_u32 s39, s6, 0x80
	s_addc_u32 s9, s7, 0
	s_add_i32 s69, 0, 0x10000
	s_cmp_eq_u32 s57, s8
	s_cselect_b32 s9, s1, s9
	s_cselect_b32 s8, s0, s39
	v_add_u32_e32 v0, s69, v156
	s_cselect_b32 s59, s35, s37
	s_cselect_b32 s58, s34, s36
	s_add_i32 s39, 0, 0x14000
	ds_read_b128 v[144:147], v0
	ds_read_b128 v[148:151], v0 offset:1024
	ds_read_b128 v[160:163], v0 offset:2048
	ds_read_b128 v[164:167], v0 offset:3072
	v_add_u32_e32 v0, s39, v156
	ds_read_b128 v[168:171], v0
	ds_read_b128 v[172:175], v0 offset:1024
	ds_read_b128 v[176:179], v0 offset:2048
	ds_read_b128 v[180:183], v0 offset:3072
	v_lshl_add_u64 v[218:219], s[6:7], 0, v[140:141]
	s_add_i32 m0, s50, 0xc000
	ds_read_b128 v[184:187], v158
	ds_read_b128 v[188:191], v158 offset:1024
	ds_read_b128 v[192:195], v158 offset:2048
	ds_read_b128 v[196:199], v158 offset:3072
	ds_read_b128 v[202:205], v158 offset:4096
	ds_read_b128 v[206:209], v158 offset:5120
	ds_read_b128 v[210:213], v158 offset:6144
	ds_read_b128 v[214:217], v158 offset:7168
	global_load_lds_dwordx4 v[218:219], off
	s_add_i32 m0, s50, 0xe000
	v_lshl_add_u64 v[218:219], s[6:7], 0, v[142:143]
	global_load_lds_dwordx4 v[218:219], off
	s_waitcnt vmcnt(8) lgkmcnt(0)
	s_barrier
	v_mfma_f32_16x16x32_bf16 v[126:129], v[144:147], v[184:187], v[126:129]
	v_mfma_f32_16x16x32_bf16 v[122:125], v[160:163], v[184:187], v[122:125]
	v_mfma_f32_16x16x32_bf16 v[110:113], v[144:147], v[192:195], v[110:113]
	v_mfma_f32_16x16x32_bf16 v[106:109], v[160:163], v[192:195], v[106:109]
	v_mfma_f32_16x16x32_bf16 v[94:97], v[144:147], v[202:205], v[94:97]
	v_mfma_f32_16x16x32_bf16 v[90:93], v[160:163], v[202:205], v[90:93]
	v_mfma_f32_16x16x32_bf16 v[78:81], v[144:147], v[210:213], v[78:81]
	v_mfma_f32_16x16x32_bf16 v[74:77], v[160:163], v[210:213], v[74:77]
	v_mfma_f32_16x16x32_bf16 v[126:129], v[148:151], v[188:191], v[126:129]
	v_mfma_f32_16x16x32_bf16 v[122:125], v[164:167], v[188:191], v[122:125]
	v_mfma_f32_16x16x32_bf16 v[110:113], v[148:151], v[196:199], v[110:113]
	v_mfma_f32_16x16x32_bf16 v[106:109], v[164:167], v[196:199], v[106:109]
	v_mfma_f32_16x16x32_bf16 v[94:97], v[148:151], v[206:209], v[94:97]
	v_mfma_f32_16x16x32_bf16 v[90:93], v[164:167], v[206:209], v[90:93]
	v_mfma_f32_16x16x32_bf16 v[78:81], v[148:151], v[214:217], v[78:81]
	v_mfma_f32_16x16x32_bf16 v[74:77], v[164:167], v[214:217], v[74:77]
	v_mfma_f32_16x16x32_bf16 v[118:121], v[168:171], v[184:187], v[118:121]
	v_mfma_f32_16x16x32_bf16 v[114:117], v[176:179], v[184:187], v[114:117]
	v_mfma_f32_16x16x32_bf16 v[102:105], v[168:171], v[192:195], v[102:105]
	v_mfma_f32_16x16x32_bf16 v[98:101], v[176:179], v[192:195], v[98:101]
	v_mfma_f32_16x16x32_bf16 v[86:89], v[168:171], v[202:205], v[86:89]
	v_mfma_f32_16x16x32_bf16 v[82:85], v[176:179], v[202:205], v[82:85]
	v_mfma_f32_16x16x32_bf16 v[70:73], v[168:171], v[210:213], v[70:73]
	v_mfma_f32_16x16x32_bf16 v[66:69], v[176:179], v[210:213], v[66:69]
	v_mfma_f32_16x16x32_bf16 v[118:121], v[172:175], v[188:191], v[118:121]
	v_mfma_f32_16x16x32_bf16 v[114:117], v[180:183], v[188:191], v[114:117]
	v_mfma_f32_16x16x32_bf16 v[102:105], v[172:175], v[196:199], v[102:105]
	v_mfma_f32_16x16x32_bf16 v[98:101], v[180:183], v[196:199], v[98:101]
	v_mfma_f32_16x16x32_bf16 v[86:89], v[172:175], v[206:209], v[86:89]
	v_mfma_f32_16x16x32_bf16 v[82:85], v[180:183], v[206:209], v[82:85]
	v_mfma_f32_16x16x32_bf16 v[70:73], v[172:175], v[214:217], v[70:73]
	v_mfma_f32_16x16x32_bf16 v[66:69], v[180:183], v[214:217], v[66:69]
	s_barrier
	s_add_i32 s69, s69, s49
	v_lshl_add_u64 v[218:219], s[58:59], 0, v[136:137]
	s_mov_b32 m0, s69
	ds_read_b128 v[184:187], v158 offset:16384
	ds_read_b128 v[188:191], v158 offset:17408
	ds_read_b128 v[192:195], v158 offset:18432
	ds_read_b128 v[196:199], v158 offset:19456
	ds_read_b128 v[202:205], v158 offset:20480
	ds_read_b128 v[206:209], v158 offset:21504
	ds_read_b128 v[210:213], v158 offset:22528
	ds_read_b128 v[214:217], v158 offset:23552
	global_load_lds_dwordx4 v[218:219], off
	s_add_i32 m0, s69, 0x2000
	v_lshl_add_u64 v[220:221], s[58:59], 0, v[132:133]
	s_add_u32 s58, s58, s47
	s_addc_u32 s59, s59, 0
	s_add_i32 s39, s39, s49
	global_load_lds_dwordx4 v[220:221], off
	v_lshl_add_u64 v[222:223], s[58:59], 0, v[136:137]
	s_mov_b32 m0, s39
	v_lshl_add_u64 v[224:225], s[58:59], 0, v[132:133]
	global_load_lds_dwordx4 v[222:223], off
	s_add_i32 m0, s39, 0x2000
	v_lshl_add_u64 v[226:227], s[8:9], 0, v[134:135]
	global_load_lds_dwordx4 v[224:225], off
	s_mov_b32 m0, s50
	v_lshl_add_u64 v[228:229], s[8:9], 0, v[130:131]
	global_load_lds_dwordx4 v[226:227], off
	s_mov_b32 m0, s51
	s_nop 0
	global_load_lds_dwordx4 v[228:229], off
	s_waitcnt vmcnt(8) lgkmcnt(0)
	s_barrier
	v_mfma_f32_16x16x32_bf16 v[62:65], v[144:147], v[184:187], v[62:65]
	v_mfma_f32_16x16x32_bf16 v[58:61], v[160:163], v[184:187], v[58:61]
	v_mfma_f32_16x16x32_bf16 v[46:49], v[144:147], v[192:195], v[46:49]
	v_mfma_f32_16x16x32_bf16 v[42:45], v[160:163], v[192:195], v[42:45]
	v_mfma_f32_16x16x32_bf16 v[30:33], v[144:147], v[202:205], v[30:33]
	v_mfma_f32_16x16x32_bf16 v[26:29], v[160:163], v[202:205], v[26:29]
	v_mfma_f32_16x16x32_bf16 v[14:17], v[144:147], v[210:213], v[14:17]
	v_mfma_f32_16x16x32_bf16 v[10:13], v[160:163], v[210:213], v[10:13]
	v_mfma_f32_16x16x32_bf16 v[62:65], v[148:151], v[188:191], v[62:65]
	v_mfma_f32_16x16x32_bf16 v[58:61], v[164:167], v[188:191], v[58:61]
	v_mfma_f32_16x16x32_bf16 v[46:49], v[148:151], v[196:199], v[46:49]
	v_mfma_f32_16x16x32_bf16 v[42:45], v[164:167], v[196:199], v[42:45]
	v_mfma_f32_16x16x32_bf16 v[30:33], v[148:151], v[206:209], v[30:33]
	v_mfma_f32_16x16x32_bf16 v[26:29], v[164:167], v[206:209], v[26:29]
	v_mfma_f32_16x16x32_bf16 v[14:17], v[148:151], v[214:217], v[14:17]
	v_mfma_f32_16x16x32_bf16 v[10:13], v[164:167], v[214:217], v[10:13]
	v_mfma_f32_16x16x32_bf16 v[54:57], v[168:171], v[184:187], v[54:57]
	v_mfma_f32_16x16x32_bf16 v[50:53], v[176:179], v[184:187], v[50:53]
	v_mfma_f32_16x16x32_bf16 v[38:41], v[168:171], v[192:195], v[38:41]
	v_mfma_f32_16x16x32_bf16 v[34:37], v[176:179], v[192:195], v[34:37]
	v_mfma_f32_16x16x32_bf16 v[22:25], v[168:171], v[202:205], v[22:25]
	v_mfma_f32_16x16x32_bf16 v[18:21], v[176:179], v[202:205], v[18:21]
	v_mfma_f32_16x16x32_bf16 v[6:9], v[168:171], v[210:213], v[6:9]
	v_mfma_f32_16x16x32_bf16 v[2:5], v[176:179], v[210:213], v[2:5]
	v_mfma_f32_16x16x32_bf16 v[54:57], v[172:175], v[188:191], v[54:57]
	v_mfma_f32_16x16x32_bf16 v[50:53], v[180:183], v[188:191], v[50:53]
	v_mfma_f32_16x16x32_bf16 v[38:41], v[172:175], v[196:199], v[38:41]
	v_mfma_f32_16x16x32_bf16 v[34:37], v[180:183], v[196:199], v[34:37]
	v_mfma_f32_16x16x32_bf16 v[22:25], v[172:175], v[206:209], v[22:25]
	v_mfma_f32_16x16x32_bf16 v[18:21], v[180:183], v[206:209], v[18:21]
	v_mfma_f32_16x16x32_bf16 v[6:9], v[172:175], v[214:217], v[6:9]
	v_mfma_f32_16x16x32_bf16 v[2:5], v[180:183], v[214:217], v[2:5]
	s_barrier
	s_add_i32 s39, 0, 0x18000
	v_add_u32_e32 v0, s39, v156
	s_add_i32 s58, 0, 0x1c000
	ds_read_b128 v[144:147], v0
	ds_read_b128 v[148:151], v0 offset:1024
	ds_read_b128 v[160:163], v0 offset:2048
	ds_read_b128 v[164:167], v0 offset:3072
	v_add_u32_e32 v0, s58, v156
	ds_read_b128 v[168:171], v0
	ds_read_b128 v[172:175], v0 offset:1024
	ds_read_b128 v[176:179], v0 offset:2048
	ds_read_b128 v[180:183], v0 offset:3072
	s_add_u32 s8, s8, s14
	s_addc_u32 s9, s9, 0
	s_mov_b32 m0, s52
	v_lshl_add_u64 v[230:231], s[8:9], 0, v[134:135]
	ds_read_b128 v[184:187], v158 offset:32768
	ds_read_b128 v[188:191], v158 offset:33792
	ds_read_b128 v[192:195], v158 offset:34816
	ds_read_b128 v[196:199], v158 offset:35840
	ds_read_b128 v[202:205], v158 offset:36864
	ds_read_b128 v[206:209], v158 offset:37888
	ds_read_b128 v[210:213], v158 offset:38912
	ds_read_b128 v[214:217], v158 offset:39936
	global_load_lds_dwordx4 v[230:231], off
	s_mov_b32 m0, s53
	v_lshl_add_u64 v[230:231], s[8:9], 0, v[130:131]
	global_load_lds_dwordx4 v[230:231], off
	s_waitcnt vmcnt(8) lgkmcnt(0)
	s_barrier
	v_mfma_f32_16x16x32_bf16 v[126:129], v[144:147], v[184:187], v[126:129]
	v_mfma_f32_16x16x32_bf16 v[122:125], v[160:163], v[184:187], v[122:125]
	v_mfma_f32_16x16x32_bf16 v[110:113], v[144:147], v[192:195], v[110:113]
	v_mfma_f32_16x16x32_bf16 v[106:109], v[160:163], v[192:195], v[106:109]
	v_mfma_f32_16x16x32_bf16 v[94:97], v[144:147], v[202:205], v[94:97]
	v_mfma_f32_16x16x32_bf16 v[90:93], v[160:163], v[202:205], v[90:93]
	v_mfma_f32_16x16x32_bf16 v[78:81], v[144:147], v[210:213], v[78:81]
	v_mfma_f32_16x16x32_bf16 v[74:77], v[160:163], v[210:213], v[74:77]
	v_mfma_f32_16x16x32_bf16 v[126:129], v[148:151], v[188:191], v[126:129]
	v_mfma_f32_16x16x32_bf16 v[122:125], v[164:167], v[188:191], v[122:125]
	v_mfma_f32_16x16x32_bf16 v[110:113], v[148:151], v[196:199], v[110:113]
	v_mfma_f32_16x16x32_bf16 v[106:109], v[164:167], v[196:199], v[106:109]
	v_mfma_f32_16x16x32_bf16 v[94:97], v[148:151], v[206:209], v[94:97]
	v_mfma_f32_16x16x32_bf16 v[90:93], v[164:167], v[206:209], v[90:93]
	v_mfma_f32_16x16x32_bf16 v[78:81], v[148:151], v[214:217], v[78:81]
	v_mfma_f32_16x16x32_bf16 v[74:77], v[164:167], v[214:217], v[74:77]
	v_mfma_f32_16x16x32_bf16 v[118:121], v[168:171], v[184:187], v[118:121]
	v_mfma_f32_16x16x32_bf16 v[114:117], v[176:179], v[184:187], v[114:117]
	v_mfma_f32_16x16x32_bf16 v[102:105], v[168:171], v[192:195], v[102:105]
	v_mfma_f32_16x16x32_bf16 v[98:101], v[176:179], v[192:195], v[98:101]
	v_mfma_f32_16x16x32_bf16 v[86:89], v[168:171], v[202:205], v[86:89]
	v_mfma_f32_16x16x32_bf16 v[82:85], v[176:179], v[202:205], v[82:85]
	v_mfma_f32_16x16x32_bf16 v[70:73], v[168:171], v[210:213], v[70:73]
	v_mfma_f32_16x16x32_bf16 v[66:69], v[176:179], v[210:213], v[66:69]
	v_mfma_f32_16x16x32_bf16 v[118:121], v[172:175], v[188:191], v[118:121]
	v_mfma_f32_16x16x32_bf16 v[114:117], v[180:183], v[188:191], v[114:117]
	v_mfma_f32_16x16x32_bf16 v[102:105], v[172:175], v[196:199], v[102:105]
	v_mfma_f32_16x16x32_bf16 v[98:101], v[180:183], v[196:199], v[98:101]
	v_mfma_f32_16x16x32_bf16 v[86:89], v[172:175], v[206:209], v[86:89]
	v_mfma_f32_16x16x32_bf16 v[82:85], v[180:183], v[206:209], v[82:85]
	v_mfma_f32_16x16x32_bf16 v[70:73], v[172:175], v[214:217], v[70:73]
	v_mfma_f32_16x16x32_bf16 v[66:69], v[180:183], v[214:217], v[66:69]
	s_barrier
	s_add_i32 s8, s39, s49
	v_lshl_add_u64 v[218:219], v[218:219], 0, s[16:17]
	s_mov_b32 m0, s8
	ds_read_b128 v[184:187], v158 offset:49152
	ds_read_b128 v[188:191], v158 offset:50176
	ds_read_b128 v[192:195], v158 offset:51200
	ds_read_b128 v[196:199], v158 offset:52224
	ds_read_b128 v[202:205], v158 offset:53248
	ds_read_b128 v[206:209], v158 offset:54272
	ds_read_b128 v[210:213], v158 offset:55296
	ds_read_b128 v[214:217], v158 offset:56320
	global_load_lds_dwordx4 v[218:219], off
	v_lshl_add_u64 v[218:219], v[220:221], 0, s[16:17]
	s_add_i32 m0, s8, 0x2000
	s_add_i32 s8, s58, s49
	global_load_lds_dwordx4 v[218:219], off
	s_mov_b32 m0, s8
	v_lshl_add_u64 v[218:219], v[222:223], 0, s[16:17]
	global_load_lds_dwordx4 v[218:219], off
	s_add_i32 m0, s8, 0x2000
	v_lshl_add_u64 v[218:219], v[224:225], 0, s[16:17]
	global_load_lds_dwordx4 v[218:219], off
	s_mov_b32 m0, s54
	v_lshl_add_u64 v[218:219], v[226:227], 0, s[16:17]
	global_load_lds_dwordx4 v[218:219], off
	s_mov_b32 m0, s55
	v_lshl_add_u64 v[218:219], v[228:229], 0, s[16:17]
	global_load_lds_dwordx4 v[218:219], off
	s_waitcnt vmcnt(8) lgkmcnt(0)
	s_barrier
	v_mfma_f32_16x16x32_bf16 v[62:65], v[144:147], v[184:187], v[62:65]
	v_mfma_f32_16x16x32_bf16 v[58:61], v[160:163], v[184:187], v[58:61]
	v_mfma_f32_16x16x32_bf16 v[46:49], v[144:147], v[192:195], v[46:49]
	v_mfma_f32_16x16x32_bf16 v[42:45], v[160:163], v[192:195], v[42:45]
	v_mfma_f32_16x16x32_bf16 v[30:33], v[144:147], v[202:205], v[30:33]
	v_mfma_f32_16x16x32_bf16 v[26:29], v[160:163], v[202:205], v[26:29]
	v_mfma_f32_16x16x32_bf16 v[14:17], v[144:147], v[210:213], v[14:17]
	v_mfma_f32_16x16x32_bf16 v[10:13], v[160:163], v[210:213], v[10:13]
	v_mfma_f32_16x16x32_bf16 v[62:65], v[148:151], v[188:191], v[62:65]
	v_mfma_f32_16x16x32_bf16 v[58:61], v[164:167], v[188:191], v[58:61]
	v_mfma_f32_16x16x32_bf16 v[46:49], v[148:151], v[196:199], v[46:49]
	v_mfma_f32_16x16x32_bf16 v[42:45], v[164:167], v[196:199], v[42:45]
	v_mfma_f32_16x16x32_bf16 v[30:33], v[148:151], v[206:209], v[30:33]
	v_mfma_f32_16x16x32_bf16 v[26:29], v[164:167], v[206:209], v[26:29]
	v_mfma_f32_16x16x32_bf16 v[14:17], v[148:151], v[214:217], v[14:17]
	v_mfma_f32_16x16x32_bf16 v[10:13], v[164:167], v[214:217], v[10:13]
	v_mfma_f32_16x16x32_bf16 v[54:57], v[168:171], v[184:187], v[54:57]
	v_mfma_f32_16x16x32_bf16 v[50:53], v[176:179], v[184:187], v[50:53]
	v_mfma_f32_16x16x32_bf16 v[38:41], v[168:171], v[192:195], v[38:41]
	v_mfma_f32_16x16x32_bf16 v[34:37], v[176:179], v[192:195], v[34:37]
	v_mfma_f32_16x16x32_bf16 v[22:25], v[168:171], v[202:205], v[22:25]
	v_mfma_f32_16x16x32_bf16 v[18:21], v[176:179], v[202:205], v[18:21]
	v_mfma_f32_16x16x32_bf16 v[6:9], v[168:171], v[210:213], v[6:9]
	v_mfma_f32_16x16x32_bf16 v[2:5], v[176:179], v[210:213], v[2:5]
	v_mfma_f32_16x16x32_bf16 v[54:57], v[172:175], v[188:191], v[54:57]
	v_mfma_f32_16x16x32_bf16 v[50:53], v[180:183], v[188:191], v[50:53]
	v_mfma_f32_16x16x32_bf16 v[38:41], v[172:175], v[196:199], v[38:41]
	v_mfma_f32_16x16x32_bf16 v[34:37], v[180:183], v[196:199], v[34:37]
	v_mfma_f32_16x16x32_bf16 v[22:25], v[172:175], v[206:209], v[22:25]
	v_mfma_f32_16x16x32_bf16 v[18:21], v[180:183], v[206:209], v[18:21]
	v_mfma_f32_16x16x32_bf16 v[6:9], v[172:175], v[214:217], v[6:9]
	v_mfma_f32_16x16x32_bf16 v[2:5], v[180:183], v[214:217], v[2:5]
	s_barrier
	s_add_u32 s6, s6, 0x100
	s_addc_u32 s7, s7, 0
	s_add_u32 s36, s36, 0x100
	s_addc_u32 s37, s37, 0
	s_cmp_ge_u32 s38, s56
	s_mov_b32 s8, s38
	s_cbranch_scc0 .LBB0_211
	s_and_b64 vcc, exec, s[28:29]
	s_cbranch_vccnz .LBB0_215
	s_lshl_b32 s8, s3, 8
	s_cmp_lt_i32 s45, 2
	s_mov_b64 s[6:7], -1
	s_cbranch_scc0 .LBB0_216

.LBB0_977:
	s_add_i32 s36, s10, 2
	s_add_u32 s37, s8, 0x80
	s_addc_u32 s11, s9, 0
	s_add_i32 s66, 0, 0x10000
	s_cmp_eq_u32 s55, s10
	s_cselect_b32 s11, s1, s11
	s_cselect_b32 s10, s0, s37
	v_add_u32_e32 v0, s66, v156
	s_cselect_b32 s59, s31, s35
	s_cselect_b32 s58, s30, s34
	s_add_i32 s37, 0, 0x14000
	ds_read_b128 v[144:147], v0
	ds_read_b128 v[148:151], v0 offset:1024
	ds_read_b128 v[160:163], v0 offset:2048
	ds_read_b128 v[164:167], v0 offset:3072
	v_add_u32_e32 v0, s37, v156
	ds_read_b128 v[168:171], v0
	ds_read_b128 v[172:175], v0 offset:1024
	ds_read_b128 v[176:179], v0 offset:2048
	ds_read_b128 v[180:183], v0 offset:3072
	v_lshl_add_u64 v[218:219], s[8:9], 0, v[140:141]
	s_add_i32 m0, s48, 0xc000
	ds_read_b128 v[184:187], v158
	ds_read_b128 v[188:191], v158 offset:1024
	ds_read_b128 v[192:195], v158 offset:2048
	ds_read_b128 v[196:199], v158 offset:3072
	ds_read_b128 v[202:205], v158 offset:4096
	ds_read_b128 v[206:209], v158 offset:5120
	ds_read_b128 v[210:213], v158 offset:6144
	ds_read_b128 v[214:217], v158 offset:7168
	global_load_lds_dwordx4 v[218:219], off
	s_add_i32 m0, s48, 0xe000
	v_lshl_add_u64 v[218:219], s[8:9], 0, v[142:143]
	global_load_lds_dwordx4 v[218:219], off
	s_waitcnt vmcnt(8) lgkmcnt(0)
	s_barrier
	v_mfma_f32_16x16x32_bf16 v[126:129], v[144:147], v[184:187], v[126:129]
	v_mfma_f32_16x16x32_bf16 v[122:125], v[160:163], v[184:187], v[122:125]
	v_mfma_f32_16x16x32_bf16 v[110:113], v[144:147], v[192:195], v[110:113]
	v_mfma_f32_16x16x32_bf16 v[106:109], v[160:163], v[192:195], v[106:109]
	v_mfma_f32_16x16x32_bf16 v[94:97], v[144:147], v[202:205], v[94:97]
	v_mfma_f32_16x16x32_bf16 v[90:93], v[160:163], v[202:205], v[90:93]
	v_mfma_f32_16x16x32_bf16 v[78:81], v[144:147], v[210:213], v[78:81]
	v_mfma_f32_16x16x32_bf16 v[74:77], v[160:163], v[210:213], v[74:77]
	v_mfma_f32_16x16x32_bf16 v[126:129], v[148:151], v[188:191], v[126:129]
	v_mfma_f32_16x16x32_bf16 v[122:125], v[164:167], v[188:191], v[122:125]
	v_mfma_f32_16x16x32_bf16 v[110:113], v[148:151], v[196:199], v[110:113]
	v_mfma_f32_16x16x32_bf16 v[106:109], v[164:167], v[196:199], v[106:109]
	v_mfma_f32_16x16x32_bf16 v[94:97], v[148:151], v[206:209], v[94:97]
	v_mfma_f32_16x16x32_bf16 v[90:93], v[164:167], v[206:209], v[90:93]
	v_mfma_f32_16x16x32_bf16 v[78:81], v[148:151], v[214:217], v[78:81]
	v_mfma_f32_16x16x32_bf16 v[74:77], v[164:167], v[214:217], v[74:77]
	v_mfma_f32_16x16x32_bf16 v[118:121], v[168:171], v[184:187], v[118:121]
	v_mfma_f32_16x16x32_bf16 v[114:117], v[176:179], v[184:187], v[114:117]
	v_mfma_f32_16x16x32_bf16 v[102:105], v[168:171], v[192:195], v[102:105]
	v_mfma_f32_16x16x32_bf16 v[98:101], v[176:179], v[192:195], v[98:101]
	v_mfma_f32_16x16x32_bf16 v[86:89], v[168:171], v[202:205], v[86:89]
	v_mfma_f32_16x16x32_bf16 v[82:85], v[176:179], v[202:205], v[82:85]
	v_mfma_f32_16x16x32_bf16 v[70:73], v[168:171], v[210:213], v[70:73]
	v_mfma_f32_16x16x32_bf16 v[66:69], v[176:179], v[210:213], v[66:69]
	v_mfma_f32_16x16x32_bf16 v[118:121], v[172:175], v[188:191], v[118:121]
	v_mfma_f32_16x16x32_bf16 v[114:117], v[180:183], v[188:191], v[114:117]
	v_mfma_f32_16x16x32_bf16 v[102:105], v[172:175], v[196:199], v[102:105]
	v_mfma_f32_16x16x32_bf16 v[98:101], v[180:183], v[196:199], v[98:101]
	v_mfma_f32_16x16x32_bf16 v[86:89], v[172:175], v[206:209], v[86:89]
	v_mfma_f32_16x16x32_bf16 v[82:85], v[180:183], v[206:209], v[82:85]
	v_mfma_f32_16x16x32_bf16 v[70:73], v[172:175], v[214:217], v[70:73]
	v_mfma_f32_16x16x32_bf16 v[66:69], v[180:183], v[214:217], v[66:69]
	s_barrier
	s_add_i32 s66, s66, s47
	v_lshl_add_u64 v[218:219], s[58:59], 0, v[136:137]
	s_mov_b32 m0, s66
	ds_read_b128 v[184:187], v158 offset:16384
	ds_read_b128 v[188:191], v158 offset:17408
	ds_read_b128 v[192:195], v158 offset:18432
	ds_read_b128 v[196:199], v158 offset:19456
	ds_read_b128 v[202:205], v158 offset:20480
	ds_read_b128 v[206:209], v158 offset:21504
	ds_read_b128 v[210:213], v158 offset:22528
	ds_read_b128 v[214:217], v158 offset:23552
	global_load_lds_dwordx4 v[218:219], off
	s_add_i32 m0, s66, 0x2000
	v_lshl_add_u64 v[220:221], s[58:59], 0, v[132:133]
	s_add_u32 s58, s58, s45
	s_addc_u32 s59, s59, 0
	s_add_i32 s37, s37, s47
	global_load_lds_dwordx4 v[220:221], off
	v_lshl_add_u64 v[222:223], s[58:59], 0, v[136:137]
	s_mov_b32 m0, s37
	v_lshl_add_u64 v[224:225], s[58:59], 0, v[132:133]
	global_load_lds_dwordx4 v[222:223], off
	s_add_i32 m0, s37, 0x2000
	v_lshl_add_u64 v[226:227], s[10:11], 0, v[134:135]
	global_load_lds_dwordx4 v[224:225], off
	s_mov_b32 m0, s48
	v_lshl_add_u64 v[228:229], s[10:11], 0, v[130:131]
	global_load_lds_dwordx4 v[226:227], off
	s_mov_b32 m0, s49
	s_nop 0
	global_load_lds_dwordx4 v[228:229], off
	s_waitcnt vmcnt(8) lgkmcnt(0)
	s_barrier
	v_mfma_f32_16x16x32_bf16 v[62:65], v[144:147], v[184:187], v[62:65]
	v_mfma_f32_16x16x32_bf16 v[58:61], v[160:163], v[184:187], v[58:61]
	v_mfma_f32_16x16x32_bf16 v[46:49], v[144:147], v[192:195], v[46:49]
	v_mfma_f32_16x16x32_bf16 v[42:45], v[160:163], v[192:195], v[42:45]
	v_mfma_f32_16x16x32_bf16 v[30:33], v[144:147], v[202:205], v[30:33]
	v_mfma_f32_16x16x32_bf16 v[26:29], v[160:163], v[202:205], v[26:29]
	v_mfma_f32_16x16x32_bf16 v[14:17], v[144:147], v[210:213], v[14:17]
	v_mfma_f32_16x16x32_bf16 v[10:13], v[160:163], v[210:213], v[10:13]
	v_mfma_f32_16x16x32_bf16 v[62:65], v[148:151], v[188:191], v[62:65]
	v_mfma_f32_16x16x32_bf16 v[58:61], v[164:167], v[188:191], v[58:61]
	v_mfma_f32_16x16x32_bf16 v[46:49], v[148:151], v[196:199], v[46:49]
	v_mfma_f32_16x16x32_bf16 v[42:45], v[164:167], v[196:199], v[42:45]
	v_mfma_f32_16x16x32_bf16 v[30:33], v[148:151], v[206:209], v[30:33]
	v_mfma_f32_16x16x32_bf16 v[26:29], v[164:167], v[206:209], v[26:29]
	v_mfma_f32_16x16x32_bf16 v[14:17], v[148:151], v[214:217], v[14:17]
	v_mfma_f32_16x16x32_bf16 v[10:13], v[164:167], v[214:217], v[10:13]
	v_mfma_f32_16x16x32_bf16 v[54:57], v[168:171], v[184:187], v[54:57]
	v_mfma_f32_16x16x32_bf16 v[50:53], v[176:179], v[184:187], v[50:53]
	v_mfma_f32_16x16x32_bf16 v[38:41], v[168:171], v[192:195], v[38:41]
	v_mfma_f32_16x16x32_bf16 v[34:37], v[176:179], v[192:195], v[34:37]
	v_mfma_f32_16x16x32_bf16 v[22:25], v[168:171], v[202:205], v[22:25]
	v_mfma_f32_16x16x32_bf16 v[18:21], v[176:179], v[202:205], v[18:21]
	v_mfma_f32_16x16x32_bf16 v[6:9], v[168:171], v[210:213], v[6:9]
	v_mfma_f32_16x16x32_bf16 v[2:5], v[176:179], v[210:213], v[2:5]
	v_mfma_f32_16x16x32_bf16 v[54:57], v[172:175], v[188:191], v[54:57]
	v_mfma_f32_16x16x32_bf16 v[50:53], v[180:183], v[188:191], v[50:53]
	v_mfma_f32_16x16x32_bf16 v[38:41], v[172:175], v[196:199], v[38:41]
	v_mfma_f32_16x16x32_bf16 v[34:37], v[180:183], v[196:199], v[34:37]
	v_mfma_f32_16x16x32_bf16 v[22:25], v[172:175], v[206:209], v[22:25]
	v_mfma_f32_16x16x32_bf16 v[18:21], v[180:183], v[206:209], v[18:21]
	v_mfma_f32_16x16x32_bf16 v[6:9], v[172:175], v[214:217], v[6:9]
	v_mfma_f32_16x16x32_bf16 v[2:5], v[180:183], v[214:217], v[2:5]
	s_barrier
	s_add_i32 s37, 0, 0x18000
	v_add_u32_e32 v0, s37, v156
	s_add_i32 s58, 0, 0x1c000
	ds_read_b128 v[144:147], v0
	ds_read_b128 v[148:151], v0 offset:1024
	ds_read_b128 v[160:163], v0 offset:2048
	ds_read_b128 v[164:167], v0 offset:3072
	v_add_u32_e32 v0, s58, v156
	ds_read_b128 v[168:171], v0
	ds_read_b128 v[172:175], v0 offset:1024
	ds_read_b128 v[176:179], v0 offset:2048
	ds_read_b128 v[180:183], v0 offset:3072
	s_add_u32 s10, s10, s12
	s_addc_u32 s11, s11, 0
	s_mov_b32 m0, s50
	v_lshl_add_u64 v[230:231], s[10:11], 0, v[134:135]
	ds_read_b128 v[184:187], v158 offset:32768
	ds_read_b128 v[188:191], v158 offset:33792
	ds_read_b128 v[192:195], v158 offset:34816
	ds_read_b128 v[196:199], v158 offset:35840
	ds_read_b128 v[202:205], v158 offset:36864
	ds_read_b128 v[206:209], v158 offset:37888
	ds_read_b128 v[210:213], v158 offset:38912
	ds_read_b128 v[214:217], v158 offset:39936
	global_load_lds_dwordx4 v[230:231], off
	s_mov_b32 m0, s51
	v_lshl_add_u64 v[230:231], s[10:11], 0, v[130:131]
	global_load_lds_dwordx4 v[230:231], off
	s_waitcnt vmcnt(8) lgkmcnt(0)
	s_barrier
	v_mfma_f32_16x16x32_bf16 v[126:129], v[144:147], v[184:187], v[126:129]
	v_mfma_f32_16x16x32_bf16 v[122:125], v[160:163], v[184:187], v[122:125]
	v_mfma_f32_16x16x32_bf16 v[110:113], v[144:147], v[192:195], v[110:113]
	v_mfma_f32_16x16x32_bf16 v[106:109], v[160:163], v[192:195], v[106:109]
	v_mfma_f32_16x16x32_bf16 v[94:97], v[144:147], v[202:205], v[94:97]
	v_mfma_f32_16x16x32_bf16 v[90:93], v[160:163], v[202:205], v[90:93]
	v_mfma_f32_16x16x32_bf16 v[78:81], v[144:147], v[210:213], v[78:81]
	v_mfma_f32_16x16x32_bf16 v[74:77], v[160:163], v[210:213], v[74:77]
	v_mfma_f32_16x16x32_bf16 v[126:129], v[148:151], v[188:191], v[126:129]
	v_mfma_f32_16x16x32_bf16 v[122:125], v[164:167], v[188:191], v[122:125]
	v_mfma_f32_16x16x32_bf16 v[110:113], v[148:151], v[196:199], v[110:113]
	v_mfma_f32_16x16x32_bf16 v[106:109], v[164:167], v[196:199], v[106:109]
	v_mfma_f32_16x16x32_bf16 v[94:97], v[148:151], v[206:209], v[94:97]
	v_mfma_f32_16x16x32_bf16 v[90:93], v[164:167], v[206:209], v[90:93]
	v_mfma_f32_16x16x32_bf16 v[78:81], v[148:151], v[214:217], v[78:81]
	v_mfma_f32_16x16x32_bf16 v[74:77], v[164:167], v[214:217], v[74:77]
	v_mfma_f32_16x16x32_bf16 v[118:121], v[168:171], v[184:187], v[118:121]
	v_mfma_f32_16x16x32_bf16 v[114:117], v[176:179], v[184:187], v[114:117]
	v_mfma_f32_16x16x32_bf16 v[102:105], v[168:171], v[192:195], v[102:105]
	v_mfma_f32_16x16x32_bf16 v[98:101], v[176:179], v[192:195], v[98:101]
	v_mfma_f32_16x16x32_bf16 v[86:89], v[168:171], v[202:205], v[86:89]
	v_mfma_f32_16x16x32_bf16 v[82:85], v[176:179], v[202:205], v[82:85]
	v_mfma_f32_16x16x32_bf16 v[70:73], v[168:171], v[210:213], v[70:73]
	v_mfma_f32_16x16x32_bf16 v[66:69], v[176:179], v[210:213], v[66:69]
	v_mfma_f32_16x16x32_bf16 v[118:121], v[172:175], v[188:191], v[118:121]
	v_mfma_f32_16x16x32_bf16 v[114:117], v[180:183], v[188:191], v[114:117]
	v_mfma_f32_16x16x32_bf16 v[102:105], v[172:175], v[196:199], v[102:105]
	v_mfma_f32_16x16x32_bf16 v[98:101], v[180:183], v[196:199], v[98:101]
	v_mfma_f32_16x16x32_bf16 v[86:89], v[172:175], v[206:209], v[86:89]
	v_mfma_f32_16x16x32_bf16 v[82:85], v[180:183], v[206:209], v[82:85]
	v_mfma_f32_16x16x32_bf16 v[70:73], v[172:175], v[214:217], v[70:73]
	v_mfma_f32_16x16x32_bf16 v[66:69], v[180:183], v[214:217], v[66:69]
	s_barrier
	s_add_i32 s10, s37, s47
	v_lshl_add_u64 v[218:219], v[218:219], 0, s[14:15]
	s_mov_b32 m0, s10
	ds_read_b128 v[184:187], v158 offset:49152
	ds_read_b128 v[188:191], v158 offset:50176
	ds_read_b128 v[192:195], v158 offset:51200
	ds_read_b128 v[196:199], v158 offset:52224
	ds_read_b128 v[202:205], v158 offset:53248
	ds_read_b128 v[206:209], v158 offset:54272
	ds_read_b128 v[210:213], v158 offset:55296
	ds_read_b128 v[214:217], v158 offset:56320
	global_load_lds_dwordx4 v[218:219], off
	v_lshl_add_u64 v[218:219], v[220:221], 0, s[14:15]
	s_add_i32 m0, s10, 0x2000
	s_add_i32 s10, s58, s47
	global_load_lds_dwordx4 v[218:219], off
	s_mov_b32 m0, s10
	v_lshl_add_u64 v[218:219], v[222:223], 0, s[14:15]
	global_load_lds_dwordx4 v[218:219], off
	s_add_i32 m0, s10, 0x2000
	v_lshl_add_u64 v[218:219], v[224:225], 0, s[14:15]
	global_load_lds_dwordx4 v[218:219], off
	s_mov_b32 m0, s53
	v_lshl_add_u64 v[218:219], v[226:227], 0, s[14:15]
	global_load_lds_dwordx4 v[218:219], off
	s_mov_b32 m0, s54
	v_lshl_add_u64 v[218:219], v[228:229], 0, s[14:15]
	global_load_lds_dwordx4 v[218:219], off
	s_waitcnt vmcnt(8) lgkmcnt(0)
	s_barrier
	v_mfma_f32_16x16x32_bf16 v[62:65], v[144:147], v[184:187], v[62:65]
	v_mfma_f32_16x16x32_bf16 v[58:61], v[160:163], v[184:187], v[58:61]
	v_mfma_f32_16x16x32_bf16 v[46:49], v[144:147], v[192:195], v[46:49]
	v_mfma_f32_16x16x32_bf16 v[42:45], v[160:163], v[192:195], v[42:45]
	v_mfma_f32_16x16x32_bf16 v[30:33], v[144:147], v[202:205], v[30:33]
	v_mfma_f32_16x16x32_bf16 v[26:29], v[160:163], v[202:205], v[26:29]
	v_mfma_f32_16x16x32_bf16 v[14:17], v[144:147], v[210:213], v[14:17]
	v_mfma_f32_16x16x32_bf16 v[10:13], v[160:163], v[210:213], v[10:13]
	v_mfma_f32_16x16x32_bf16 v[62:65], v[148:151], v[188:191], v[62:65]
	v_mfma_f32_16x16x32_bf16 v[58:61], v[164:167], v[188:191], v[58:61]
	v_mfma_f32_16x16x32_bf16 v[46:49], v[148:151], v[196:199], v[46:49]
	v_mfma_f32_16x16x32_bf16 v[42:45], v[164:167], v[196:199], v[42:45]
	v_mfma_f32_16x16x32_bf16 v[30:33], v[148:151], v[206:209], v[30:33]
	v_mfma_f32_16x16x32_bf16 v[26:29], v[164:167], v[206:209], v[26:29]
	v_mfma_f32_16x16x32_bf16 v[14:17], v[148:151], v[214:217], v[14:17]
	v_mfma_f32_16x16x32_bf16 v[10:13], v[164:167], v[214:217], v[10:13]
	v_mfma_f32_16x16x32_bf16 v[54:57], v[168:171], v[184:187], v[54:57]
	v_mfma_f32_16x16x32_bf16 v[50:53], v[176:179], v[184:187], v[50:53]
	v_mfma_f32_16x16x32_bf16 v[38:41], v[168:171], v[192:195], v[38:41]
	v_mfma_f32_16x16x32_bf16 v[34:37], v[176:179], v[192:195], v[34:37]
	v_mfma_f32_16x16x32_bf16 v[22:25], v[168:171], v[202:205], v[22:25]
	v_mfma_f32_16x16x32_bf16 v[18:21], v[176:179], v[202:205], v[18:21]
	v_mfma_f32_16x16x32_bf16 v[6:9], v[168:171], v[210:213], v[6:9]
	v_mfma_f32_16x16x32_bf16 v[2:5], v[176:179], v[210:213], v[2:5]
	v_mfma_f32_16x16x32_bf16 v[54:57], v[172:175], v[188:191], v[54:57]
	v_mfma_f32_16x16x32_bf16 v[50:53], v[180:183], v[188:191], v[50:53]
	v_mfma_f32_16x16x32_bf16 v[38:41], v[172:175], v[196:199], v[38:41]
	v_mfma_f32_16x16x32_bf16 v[34:37], v[180:183], v[196:199], v[34:37]
	v_mfma_f32_16x16x32_bf16 v[22:25], v[172:175], v[206:209], v[22:25]
	v_mfma_f32_16x16x32_bf16 v[18:21], v[180:183], v[206:209], v[18:21]
	v_mfma_f32_16x16x32_bf16 v[6:9], v[172:175], v[214:217], v[6:9]
	v_mfma_f32_16x16x32_bf16 v[2:5], v[180:183], v[214:217], v[2:5]
	s_barrier
	s_add_u32 s8, s8, 0x100
	s_addc_u32 s9, s9, 0
	s_add_u32 s34, s34, 0x100
	s_addc_u32 s35, s35, 0
	s_cmp_ge_u32 s36, s52
	s_mov_b32 s10, s36
	s_cbranch_scc0 .LBB0_977

.Lg2_first:
	s_mov_b32 s32, 0
	s_add_i32 s36, s10, 2
	s_add_u32 s37, s8, 0x80
	s_addc_u32 s11, s9, 0
	s_add_i32 s66, 0, 0x10000
	s_cmp_eq_u32 s55, s10
	s_cselect_b32 s11, s1, s11
	s_cselect_b32 s10, s0, s37
	v_add_u32_e32 v0, s66, v156
	s_cselect_b32 s59, s31, s35
	s_cselect_b32 s58, s30, s34
	s_add_i32 s37, 0, 0x14000
	ds_read_b128 v[144:147], v0
	ds_read_b128 v[148:151], v0 offset:1024
	ds_read_b128 v[160:163], v0 offset:2048
	ds_read_b128 v[164:167], v0 offset:3072
	v_add_u32_e32 v0, s37, v156
	ds_read_b128 v[168:171], v0
	ds_read_b128 v[172:175], v0 offset:1024
	ds_read_b128 v[176:179], v0 offset:2048
	ds_read_b128 v[180:183], v0 offset:3072
	v_lshl_add_u64 v[218:219], s[8:9], 0, v[140:141]
	s_add_i32 m0, s48, 0xc000
	ds_read_b128 v[184:187], v158
	ds_read_b128 v[188:191], v158 offset:1024
	ds_read_b128 v[192:195], v158 offset:2048
	ds_read_b128 v[196:199], v158 offset:3072
	ds_read_b128 v[202:205], v158 offset:4096
	ds_read_b128 v[206:209], v158 offset:5120
	ds_read_b128 v[210:213], v158 offset:6144
	ds_read_b128 v[214:217], v158 offset:7168
	global_load_lds_dwordx4 v[218:219], off
	s_add_i32 m0, s48, 0xe000
	v_lshl_add_u64 v[218:219], s[8:9], 0, v[142:143]
	global_load_lds_dwordx4 v[218:219], off
	s_waitcnt lgkmcnt(0)
	s_barrier
	v_mfma_f32_16x16x32_bf16 v[126:129], v[144:147], v[184:187], 0
	v_mfma_f32_16x16x32_bf16 v[122:125], v[160:163], v[184:187], 0
	v_mfma_f32_16x16x32_bf16 v[110:113], v[144:147], v[192:195], 0
	v_mfma_f32_16x16x32_bf16 v[106:109], v[160:163], v[192:195], 0
	v_mfma_f32_16x16x32_bf16 v[94:97], v[144:147], v[202:205], 0
	v_mfma_f32_16x16x32_bf16 v[90:93], v[160:163], v[202:205], 0
	v_mfma_f32_16x16x32_bf16 v[78:81], v[144:147], v[210:213], 0
	v_mfma_f32_16x16x32_bf16 v[74:77], v[160:163], v[210:213], 0
	v_mfma_f32_16x16x32_bf16 v[126:129], v[148:151], v[188:191], v[126:129]
	v_mfma_f32_16x16x32_bf16 v[122:125], v[164:167], v[188:191], v[122:125]
	v_mfma_f32_16x16x32_bf16 v[110:113], v[148:151], v[196:199], v[110:113]
	v_mfma_f32_16x16x32_bf16 v[106:109], v[164:167], v[196:199], v[106:109]
	v_mfma_f32_16x16x32_bf16 v[94:97], v[148:151], v[206:209], v[94:97]
	v_mfma_f32_16x16x32_bf16 v[90:93], v[164:167], v[206:209], v[90:93]
	v_mfma_f32_16x16x32_bf16 v[78:81], v[148:151], v[214:217], v[78:81]
	v_mfma_f32_16x16x32_bf16 v[74:77], v[164:167], v[214:217], v[74:77]
	v_mfma_f32_16x16x32_bf16 v[118:121], v[168:171], v[184:187], 0
	v_mfma_f32_16x16x32_bf16 v[114:117], v[176:179], v[184:187], 0
	v_mfma_f32_16x16x32_bf16 v[102:105], v[168:171], v[192:195], 0
	v_mfma_f32_16x16x32_bf16 v[98:101], v[176:179], v[192:195], 0
	v_mfma_f32_16x16x32_bf16 v[86:89], v[168:171], v[202:205], 0
	v_mfma_f32_16x16x32_bf16 v[82:85], v[176:179], v[202:205], 0
	v_mfma_f32_16x16x32_bf16 v[70:73], v[168:171], v[210:213], 0
	v_mfma_f32_16x16x32_bf16 v[66:69], v[176:179], v[210:213], 0
	v_mfma_f32_16x16x32_bf16 v[118:121], v[172:175], v[188:191], v[118:121]
	v_mfma_f32_16x16x32_bf16 v[114:117], v[180:183], v[188:191], v[114:117]
	v_mfma_f32_16x16x32_bf16 v[102:105], v[172:175], v[196:199], v[102:105]
	v_mfma_f32_16x16x32_bf16 v[98:101], v[180:183], v[196:199], v[98:101]
	v_mfma_f32_16x16x32_bf16 v[86:89], v[172:175], v[206:209], v[86:89]
	v_mfma_f32_16x16x32_bf16 v[82:85], v[180:183], v[206:209], v[82:85]
	v_mfma_f32_16x16x32_bf16 v[70:73], v[172:175], v[214:217], v[70:73]
	v_mfma_f32_16x16x32_bf16 v[66:69], v[180:183], v[214:217], v[66:69]
	s_barrier
	s_add_i32 s66, s66, s47
	v_lshl_add_u64 v[218:219], s[58:59], 0, v[136:137]
	s_mov_b32 m0, s66
	ds_read_b128 v[184:187], v158 offset:16384
	ds_read_b128 v[188:191], v158 offset:17408
	ds_read_b128 v[192:195], v158 offset:18432
	ds_read_b128 v[196:199], v158 offset:19456
	ds_read_b128 v[202:205], v158 offset:20480
	ds_read_b128 v[206:209], v158 offset:21504
	ds_read_b128 v[210:213], v158 offset:22528
	ds_read_b128 v[214:217], v158 offset:23552
	global_load_lds_dwordx4 v[218:219], off
	s_add_i32 m0, s66, 0x2000
	v_lshl_add_u64 v[220:221], s[58:59], 0, v[132:133]
	s_add_u32 s58, s58, s45
	s_addc_u32 s59, s59, 0
	s_add_i32 s37, s37, s47
	global_load_lds_dwordx4 v[220:221], off
	v_lshl_add_u64 v[222:223], s[58:59], 0, v[136:137]
	s_mov_b32 m0, s37
	v_lshl_add_u64 v[224:225], s[58:59], 0, v[132:133]
	global_load_lds_dwordx4 v[222:223], off
	s_add_i32 m0, s37, 0x2000
	v_lshl_add_u64 v[226:227], s[10:11], 0, v[134:135]
	global_load_lds_dwordx4 v[224:225], off
	s_mov_b32 m0, s48
	v_lshl_add_u64 v[228:229], s[10:11], 0, v[130:131]
	global_load_lds_dwordx4 v[226:227], off
	s_mov_b32 m0, s49
	s_nop 0
	global_load_lds_dwordx4 v[228:229], off
	s_waitcnt lgkmcnt(0)
	s_barrier
	v_mfma_f32_16x16x32_bf16 v[62:65], v[144:147], v[184:187], 0
	v_mfma_f32_16x16x32_bf16 v[58:61], v[160:163], v[184:187], 0
	v_mfma_f32_16x16x32_bf16 v[46:49], v[144:147], v[192:195], 0
	v_mfma_f32_16x16x32_bf16 v[42:45], v[160:163], v[192:195], 0
	v_mfma_f32_16x16x32_bf16 v[30:33], v[144:147], v[202:205], 0
	v_mfma_f32_16x16x32_bf16 v[26:29], v[160:163], v[202:205], 0
	v_mfma_f32_16x16x32_bf16 v[14:17], v[144:147], v[210:213], 0
	v_mfma_f32_16x16x32_bf16 v[10:13], v[160:163], v[210:213], 0
	v_mfma_f32_16x16x32_bf16 v[62:65], v[148:151], v[188:191], v[62:65]
	v_mfma_f32_16x16x32_bf16 v[58:61], v[164:167], v[188:191], v[58:61]
	v_mfma_f32_16x16x32_bf16 v[46:49], v[148:151], v[196:199], v[46:49]
	v_mfma_f32_16x16x32_bf16 v[42:45], v[164:167], v[196:199], v[42:45]
	v_mfma_f32_16x16x32_bf16 v[30:33], v[148:151], v[206:209], v[30:33]
	v_mfma_f32_16x16x32_bf16 v[26:29], v[164:167], v[206:209], v[26:29]
	v_mfma_f32_16x16x32_bf16 v[14:17], v[148:151], v[214:217], v[14:17]
	v_mfma_f32_16x16x32_bf16 v[10:13], v[164:167], v[214:217], v[10:13]
	v_mfma_f32_16x16x32_bf16 v[54:57], v[168:171], v[184:187], 0
	v_mfma_f32_16x16x32_bf16 v[50:53], v[176:179], v[184:187], 0
	v_mfma_f32_16x16x32_bf16 v[38:41], v[168:171], v[192:195], 0
	v_mfma_f32_16x16x32_bf16 v[34:37], v[176:179], v[192:195], 0
	v_mfma_f32_16x16x32_bf16 v[22:25], v[168:171], v[202:205], 0
	v_mfma_f32_16x16x32_bf16 v[18:21], v[176:179], v[202:205], 0
	v_mfma_f32_16x16x32_bf16 v[6:9], v[168:171], v[210:213], 0
	v_mfma_f32_16x16x32_bf16 v[2:5], v[176:179], v[210:213], 0
	v_mfma_f32_16x16x32_bf16 v[54:57], v[172:175], v[188:191], v[54:57]
	v_mfma_f32_16x16x32_bf16 v[50:53], v[180:183], v[188:191], v[50:53]
	v_mfma_f32_16x16x32_bf16 v[38:41], v[172:175], v[196:199], v[38:41]
	v_mfma_f32_16x16x32_bf16 v[34:37], v[180:183], v[196:199], v[34:37]
	v_mfma_f32_16x16x32_bf16 v[22:25], v[172:175], v[206:209], v[22:25]
	v_mfma_f32_16x16x32_bf16 v[18:21], v[180:183], v[206:209], v[18:21]
	v_mfma_f32_16x16x32_bf16 v[6:9], v[172:175], v[214:217], v[6:9]
	v_mfma_f32_16x16x32_bf16 v[2:5], v[180:183], v[214:217], v[2:5]
	s_barrier
	s_add_i32 s37, 0, 0x18000
	v_add_u32_e32 v0, s37, v156
	s_add_i32 s58, 0, 0x1c000
	ds_read_b128 v[144:147], v0
	ds_read_b128 v[148:151], v0 offset:1024
	ds_read_b128 v[160:163], v0 offset:2048
	ds_read_b128 v[164:167], v0 offset:3072
	v_add_u32_e32 v0, s58, v156
	ds_read_b128 v[168:171], v0
	ds_read_b128 v[172:175], v0 offset:1024
	ds_read_b128 v[176:179], v0 offset:2048
	ds_read_b128 v[180:183], v0 offset:3072
	s_add_u32 s10, s10, s12
	s_addc_u32 s11, s11, 0
	s_mov_b32 m0, s50
	v_lshl_add_u64 v[230:231], s[10:11], 0, v[134:135]
	ds_read_b128 v[184:187], v158 offset:32768
	ds_read_b128 v[188:191], v158 offset:33792
	ds_read_b128 v[192:195], v158 offset:34816
	ds_read_b128 v[196:199], v158 offset:35840
	ds_read_b128 v[202:205], v158 offset:36864
	ds_read_b128 v[206:209], v158 offset:37888
	ds_read_b128 v[210:213], v158 offset:38912
	ds_read_b128 v[214:217], v158 offset:39936
	global_load_lds_dwordx4 v[230:231], off
	s_mov_b32 m0, s51
	v_lshl_add_u64 v[230:231], s[10:11], 0, v[130:131]
	global_load_lds_dwordx4 v[230:231], off
	s_waitcnt vmcnt(8) lgkmcnt(0)
	s_barrier
	v_mfma_f32_16x16x32_bf16 v[126:129], v[144:147], v[184:187], v[126:129]
	v_mfma_f32_16x16x32_bf16 v[122:125], v[160:163], v[184:187], v[122:125]
	v_mfma_f32_16x16x32_bf16 v[110:113], v[144:147], v[192:195], v[110:113]
	v_mfma_f32_16x16x32_bf16 v[106:109], v[160:163], v[192:195], v[106:109]
	v_mfma_f32_16x16x32_bf16 v[94:97], v[144:147], v[202:205], v[94:97]
	v_mfma_f32_16x16x32_bf16 v[90:93], v[160:163], v[202:205], v[90:93]
	v_mfma_f32_16x16x32_bf16 v[78:81], v[144:147], v[210:213], v[78:81]
	v_mfma_f32_16x16x32_bf16 v[74:77], v[160:163], v[210:213], v[74:77]
	v_mfma_f32_16x16x32_bf16 v[126:129], v[148:151], v[188:191], v[126:129]
	v_mfma_f32_16x16x32_bf16 v[122:125], v[164:167], v[188:191], v[122:125]
	v_mfma_f32_16x16x32_bf16 v[110:113], v[148:151], v[196:199], v[110:113]
	v_mfma_f32_16x16x32_bf16 v[106:109], v[164:167], v[196:199], v[106:109]
	v_mfma_f32_16x16x32_bf16 v[94:97], v[148:151], v[206:209], v[94:97]
	v_mfma_f32_16x16x32_bf16 v[90:93], v[164:167], v[206:209], v[90:93]
	v_mfma_f32_16x16x32_bf16 v[78:81], v[148:151], v[214:217], v[78:81]
	v_mfma_f32_16x16x32_bf16 v[74:77], v[164:167], v[214:217], v[74:77]
	v_mfma_f32_16x16x32_bf16 v[118:121], v[168:171], v[184:187], v[118:121]
	v_mfma_f32_16x16x32_bf16 v[114:117], v[176:179], v[184:187], v[114:117]
	v_mfma_f32_16x16x32_bf16 v[102:105], v[168:171], v[192:195], v[102:105]
	v_mfma_f32_16x16x32_bf16 v[98:101], v[176:179], v[192:195], v[98:101]
	v_mfma_f32_16x16x32_bf16 v[86:89], v[168:171], v[202:205], v[86:89]
	v_mfma_f32_16x16x32_bf16 v[82:85], v[176:179], v[202:205], v[82:85]
	v_mfma_f32_16x16x32_bf16 v[70:73], v[168:171], v[210:213], v[70:73]
	v_mfma_f32_16x16x32_bf16 v[66:69], v[176:179], v[210:213], v[66:69]
	v_mfma_f32_16x16x32_bf16 v[118:121], v[172:175], v[188:191], v[118:121]
	v_mfma_f32_16x16x32_bf16 v[114:117], v[180:183], v[188:191], v[114:117]
	v_mfma_f32_16x16x32_bf16 v[102:105], v[172:175], v[196:199], v[102:105]
	v_mfma_f32_16x16x32_bf16 v[98:101], v[180:183], v[196:199], v[98:101]
	v_mfma_f32_16x16x32_bf16 v[86:89], v[172:175], v[206:209], v[86:89]
	v_mfma_f32_16x16x32_bf16 v[82:85], v[180:183], v[206:209], v[82:85]
	v_mfma_f32_16x16x32_bf16 v[70:73], v[172:175], v[214:217], v[70:73]
	v_mfma_f32_16x16x32_bf16 v[66:69], v[180:183], v[214:217], v[66:69]
	s_barrier
	s_add_i32 s10, s37, s47
	v_lshl_add_u64 v[218:219], v[218:219], 0, s[14:15]
	s_mov_b32 m0, s10
	ds_read_b128 v[184:187], v158 offset:49152
	ds_read_b128 v[188:191], v158 offset:50176
	ds_read_b128 v[192:195], v158 offset:51200
	ds_read_b128 v[196:199], v158 offset:52224
	ds_read_b128 v[202:205], v158 offset:53248
	ds_read_b128 v[206:209], v158 offset:54272
	ds_read_b128 v[210:213], v158 offset:55296
	ds_read_b128 v[214:217], v158 offset:56320
	global_load_lds_dwordx4 v[218:219], off
	v_lshl_add_u64 v[218:219], v[220:221], 0, s[14:15]
	s_add_i32 m0, s10, 0x2000
	s_add_i32 s10, s58, s47
	global_load_lds_dwordx4 v[218:219], off
	s_mov_b32 m0, s10
	v_lshl_add_u64 v[218:219], v[222:223], 0, s[14:15]
	global_load_lds_dwordx4 v[218:219], off
	s_add_i32 m0, s10, 0x2000
	v_lshl_add_u64 v[218:219], v[224:225], 0, s[14:15]
	global_load_lds_dwordx4 v[218:219], off
	s_mov_b32 m0, s53
	v_lshl_add_u64 v[218:219], v[226:227], 0, s[14:15]
	global_load_lds_dwordx4 v[218:219], off
	s_mov_b32 m0, s54
	v_lshl_add_u64 v[218:219], v[228:229], 0, s[14:15]
	global_load_lds_dwordx4 v[218:219], off
	s_waitcnt vmcnt(8) lgkmcnt(0)
	s_barrier
	v_mfma_f32_16x16x32_bf16 v[62:65], v[144:147], v[184:187], v[62:65]
	v_mfma_f32_16x16x32_bf16 v[58:61], v[160:163], v[184:187], v[58:61]
	v_mfma_f32_16x16x32_bf16 v[46:49], v[144:147], v[192:195], v[46:49]
	v_mfma_f32_16x16x32_bf16 v[42:45], v[160:163], v[192:195], v[42:45]
	v_mfma_f32_16x16x32_bf16 v[30:33], v[144:147], v[202:205], v[30:33]
	v_mfma_f32_16x16x32_bf16 v[26:29], v[160:163], v[202:205], v[26:29]
	v_mfma_f32_16x16x32_bf16 v[14:17], v[144:147], v[210:213], v[14:17]
	v_mfma_f32_16x16x32_bf16 v[10:13], v[160:163], v[210:213], v[10:13]
	v_mfma_f32_16x16x32_bf16 v[62:65], v[148:151], v[188:191], v[62:65]
	v_mfma_f32_16x16x32_bf16 v[58:61], v[164:167], v[188:191], v[58:61]
	v_mfma_f32_16x16x32_bf16 v[46:49], v[148:151], v[196:199], v[46:49]
	v_mfma_f32_16x16x32_bf16 v[42:45], v[164:167], v[196:199], v[42:45]
	v_mfma_f32_16x16x32_bf16 v[30:33], v[148:151], v[206:209], v[30:33]
	v_mfma_f32_16x16x32_bf16 v[26:29], v[164:167], v[206:209], v[26:29]
	v_mfma_f32_16x16x32_bf16 v[14:17], v[148:151], v[214:217], v[14:17]
	v_mfma_f32_16x16x32_bf16 v[10:13], v[164:167], v[214:217], v[10:13]
	v_mfma_f32_16x16x32_bf16 v[54:57], v[168:171], v[184:187], v[54:57]
	v_mfma_f32_16x16x32_bf16 v[50:53], v[176:179], v[184:187], v[50:53]
	v_mfma_f32_16x16x32_bf16 v[38:41], v[168:171], v[192:195], v[38:41]
	v_mfma_f32_16x16x32_bf16 v[34:37], v[176:179], v[192:195], v[34:37]
	v_mfma_f32_16x16x32_bf16 v[22:25], v[168:171], v[202:205], v[22:25]
	v_mfma_f32_16x16x32_bf16 v[18:21], v[176:179], v[202:205], v[18:21]
	v_mfma_f32_16x16x32_bf16 v[6:9], v[168:171], v[210:213], v[6:9]
	v_mfma_f32_16x16x32_bf16 v[2:5], v[176:179], v[210:213], v[2:5]
	v_mfma_f32_16x16x32_bf16 v[54:57], v[172:175], v[188:191], v[54:57]
	v_mfma_f32_16x16x32_bf16 v[50:53], v[180:183], v[188:191], v[50:53]
	v_mfma_f32_16x16x32_bf16 v[38:41], v[172:175], v[196:199], v[38:41]
	v_mfma_f32_16x16x32_bf16 v[34:37], v[180:183], v[196:199], v[34:37]
	v_mfma_f32_16x16x32_bf16 v[22:25], v[172:175], v[206:209], v[22:25]
	v_mfma_f32_16x16x32_bf16 v[18:21], v[180:183], v[206:209], v[18:21]
	v_mfma_f32_16x16x32_bf16 v[6:9], v[172:175], v[214:217], v[6:9]
	v_mfma_f32_16x16x32_bf16 v[2:5], v[180:183], v[214:217], v[2:5]
	s_barrier
	s_add_u32 s8, s8, 0x100
	s_addc_u32 s9, s9, 0
	s_add_u32 s34, s34, 0x100
	s_addc_u32 s35, s35, 0
	s_cmp_ge_u32 s36, s52
	s_mov_b32 s10, s36
	s_cbranch_scc0 .LBB0_977
	s_branch .Lg2_after
